# FFN-in layer-1 K loops: two LDS-DMA pieces moved from the SP2(t) load segment to the next SP1 segment (4/4 instead of 6/2), SP2 wait vmcnt(6)
# speedup vs baseline: 1.0021x; 1.0015x over previous
.LBB0_1563:
	ds_read_b128 v[168:171], v165
	ds_read_b128 v[172:175], v165 offset:1024
	ds_read_b128 v[176:179], v165 offset:2048
	ds_read_b128 v[180:183], v165 offset:3072
	ds_read_b128 v[184:187], v166
	ds_read_b128 v[188:191], v166 offset:1024
	ds_read_b128 v[192:195], v166 offset:2048
	ds_read_b128 v[196:199], v166 offset:3072
	s_add_u32 s22, s20, 0xfffc0080
	s_addc_u32 s23, s21, -1
	s_cmp_eq_u32 s49, 12
	s_cselect_b32 s25, s9, s23
	s_cselect_b32 s24, s45, s22
	s_cselect_b32 s23, s11, s48
	s_cselect_b32 s22, s46, s47
	v_lshl_add_u64 v[162:163], s[20:21], 0, v[156:157]
	s_add_i32 m0, s17, 0xc000
	ds_read_b128 v[210:213], v167
	ds_read_b128 v[214:217], v167 offset:1024
	ds_read_b128 v[218:221], v167 offset:2048
	ds_read_b128 v[222:225], v167 offset:3072
	ds_read_b128 v[226:229], v167 offset:4096
	ds_read_b128 v[230:233], v167 offset:5120
	ds_read_b128 v[234:237], v167 offset:6144
	ds_read_b128 v[238:241], v167 offset:7168
	global_load_lds_dwordx4 v[162:163], off
	v_lshl_add_u64 v[162:163], s[20:21], 0, v[154:155]
	s_add_i32 m0, s17, 0xe000
	s_nop 0
	global_load_lds_dwordx4 v[162:163], off
	s_waitcnt vmcnt(8)
	s_waitcnt lgkmcnt(0)
	s_barrier
	s_setprio 1
	s_waitcnt lgkmcnt(0)
	v_mfma_f32_16x16x32_bf16 v[124:127], v[168:171], v[210:213], v[124:127]
	v_mfma_f32_16x16x32_bf16 v[116:119], v[176:179], v[210:213], v[116:119]
	v_mfma_f32_16x16x32_bf16 v[108:111], v[168:171], v[218:221], v[108:111]
	v_mfma_f32_16x16x32_bf16 v[100:103], v[176:179], v[218:221], v[100:103]
	v_mfma_f32_16x16x32_bf16 v[92:95], v[168:171], v[226:229], v[92:95]
	v_mfma_f32_16x16x32_bf16 v[84:87], v[176:179], v[226:229], v[84:87]
	v_mfma_f32_16x16x32_bf16 v[76:79], v[168:171], v[234:237], v[76:79]
	v_mfma_f32_16x16x32_bf16 v[68:71], v[176:179], v[234:237], v[68:71]
	v_mfma_f32_16x16x32_bf16 v[124:127], v[172:175], v[214:217], v[124:127]
	v_mfma_f32_16x16x32_bf16 v[116:119], v[180:183], v[214:217], v[116:119]
	v_mfma_f32_16x16x32_bf16 v[108:111], v[172:175], v[222:225], v[108:111]
	v_mfma_f32_16x16x32_bf16 v[100:103], v[180:183], v[222:225], v[100:103]
	v_mfma_f32_16x16x32_bf16 v[92:95], v[172:175], v[230:233], v[92:95]
	v_mfma_f32_16x16x32_bf16 v[84:87], v[180:183], v[230:233], v[84:87]
	v_mfma_f32_16x16x32_bf16 v[76:79], v[172:175], v[238:241], v[76:79]
	v_mfma_f32_16x16x32_bf16 v[68:71], v[180:183], v[238:241], v[68:71]
	s_setprio 0
	s_setprio 1
	v_mfma_f32_16x16x32_bf16 v[120:123], v[184:187], v[210:213], v[120:123]
	v_mfma_f32_16x16x32_bf16 v[112:115], v[192:195], v[210:213], v[112:115]
	v_mfma_f32_16x16x32_bf16 v[104:107], v[184:187], v[218:221], v[104:107]
	v_mfma_f32_16x16x32_bf16 v[96:99], v[192:195], v[218:221], v[96:99]
	v_mfma_f32_16x16x32_bf16 v[88:91], v[184:187], v[226:229], v[88:91]
	v_mfma_f32_16x16x32_bf16 v[80:83], v[192:195], v[226:229], v[80:83]
	v_mfma_f32_16x16x32_bf16 v[72:75], v[184:187], v[234:237], v[72:75]
	v_mfma_f32_16x16x32_bf16 v[64:67], v[192:195], v[234:237], v[64:67]
	v_mfma_f32_16x16x32_bf16 v[120:123], v[188:191], v[214:217], v[120:123]
	v_mfma_f32_16x16x32_bf16 v[112:115], v[196:199], v[214:217], v[112:115]
	v_mfma_f32_16x16x32_bf16 v[104:107], v[188:191], v[222:225], v[104:107]
	v_mfma_f32_16x16x32_bf16 v[96:99], v[196:199], v[222:225], v[96:99]
	v_mfma_f32_16x16x32_bf16 v[88:91], v[188:191], v[230:233], v[88:91]
	v_mfma_f32_16x16x32_bf16 v[80:83], v[196:199], v[230:233], v[80:83]
	v_mfma_f32_16x16x32_bf16 v[72:75], v[188:191], v[238:241], v[72:75]
	v_mfma_f32_16x16x32_bf16 v[64:67], v[196:199], v[238:241], v[64:67]
	s_setprio 0
	s_barrier
	s_add_i32 s50, s43, s33
	v_lshl_add_u64 v[162:163], s[22:23], 0, v[132:133]
	s_mov_b32 m0, s50
	ds_read_b128 v[210:213], v167 offset:16384
	ds_read_b128 v[214:217], v167 offset:17408
	ds_read_b128 v[218:221], v167 offset:18432
	ds_read_b128 v[222:225], v167 offset:19456
	ds_read_b128 v[226:229], v167 offset:20480
	ds_read_b128 v[230:233], v167 offset:21504
	ds_read_b128 v[234:237], v167 offset:22528
	ds_read_b128 v[238:241], v167 offset:23552
	global_load_lds_dwordx4 v[162:163], off
	s_add_i32 m0, s50, 0x2000
	s_add_u32 s50, s22, 0x4000
	v_lshl_add_u64 v[162:163], s[22:23], 0, v[128:129]
	s_addc_u32 s51, s23, 0
	s_add_i32 s52, s44, s33
	global_load_lds_dwordx4 v[162:163], off
	v_lshl_add_u64 v[162:163], s[50:51], 0, v[132:133]
	s_mov_b32 m0, s52
	v_lshl_add_u64 v[200:201], s[24:25], 0, v[130:131]
	global_load_lds_dwordx4 v[162:163], off
	v_lshl_add_u64 v[162:163], s[50:51], 0, v[128:129]
	s_add_i32 m0, s52, 0x2000
	s_nop 0
	global_load_lds_dwordx4 v[162:163], off
	v_lshl_add_u64 v[162:163], s[24:25], 0, v[134:135]
	s_waitcnt vmcnt(6)
	s_waitcnt lgkmcnt(0)
	s_barrier
	s_setprio 1
	s_waitcnt lgkmcnt(0)
	v_mfma_f32_16x16x32_bf16 v[60:63], v[168:171], v[210:213], v[60:63]
	v_mfma_f32_16x16x32_bf16 v[52:55], v[176:179], v[210:213], v[52:55]
	v_mfma_f32_16x16x32_bf16 v[44:47], v[168:171], v[218:221], v[44:47]
	v_mfma_f32_16x16x32_bf16 v[36:39], v[176:179], v[218:221], v[36:39]
	v_mfma_f32_16x16x32_bf16 v[28:31], v[168:171], v[226:229], v[28:31]
	v_mfma_f32_16x16x32_bf16 v[20:23], v[176:179], v[226:229], v[20:23]
	v_mfma_f32_16x16x32_bf16 v[12:15], v[168:171], v[234:237], v[12:15]
	v_mfma_f32_16x16x32_bf16 v[4:7], v[176:179], v[234:237], v[4:7]
	v_mfma_f32_16x16x32_bf16 v[60:63], v[172:175], v[214:217], v[60:63]
	v_mfma_f32_16x16x32_bf16 v[52:55], v[180:183], v[214:217], v[52:55]
	v_mfma_f32_16x16x32_bf16 v[44:47], v[172:175], v[222:225], v[44:47]
	v_mfma_f32_16x16x32_bf16 v[36:39], v[180:183], v[222:225], v[36:39]
	v_mfma_f32_16x16x32_bf16 v[28:31], v[172:175], v[230:233], v[28:31]
	v_mfma_f32_16x16x32_bf16 v[20:23], v[180:183], v[230:233], v[20:23]
	v_mfma_f32_16x16x32_bf16 v[12:15], v[172:175], v[238:241], v[12:15]
	v_mfma_f32_16x16x32_bf16 v[4:7], v[180:183], v[238:241], v[4:7]
	s_setprio 0
	s_setprio 1
	v_mfma_f32_16x16x32_bf16 v[56:59], v[184:187], v[210:213], v[56:59]
	v_mfma_f32_16x16x32_bf16 v[48:51], v[192:195], v[210:213], v[48:51]
	v_mfma_f32_16x16x32_bf16 v[40:43], v[184:187], v[218:221], v[40:43]
	v_mfma_f32_16x16x32_bf16 v[32:35], v[192:195], v[218:221], v[32:35]
	v_mfma_f32_16x16x32_bf16 v[24:27], v[184:187], v[226:229], v[24:27]
	v_mfma_f32_16x16x32_bf16 v[16:19], v[192:195], v[226:229], v[16:19]
	v_mfma_f32_16x16x32_bf16 v[8:11], v[184:187], v[234:237], v[8:11]
	v_mfma_f32_16x16x32_bf16 v[0:3], v[192:195], v[234:237], v[0:3]
	v_mfma_f32_16x16x32_bf16 v[56:59], v[188:191], v[214:217], v[56:59]
	v_mfma_f32_16x16x32_bf16 v[48:51], v[196:199], v[214:217], v[48:51]
	v_mfma_f32_16x16x32_bf16 v[40:43], v[188:191], v[222:225], v[40:43]
	v_mfma_f32_16x16x32_bf16 v[32:35], v[196:199], v[222:225], v[32:35]
	v_mfma_f32_16x16x32_bf16 v[24:27], v[188:191], v[230:233], v[24:27]
	v_mfma_f32_16x16x32_bf16 v[16:19], v[196:199], v[230:233], v[16:19]
	v_mfma_f32_16x16x32_bf16 v[8:11], v[188:191], v[238:241], v[8:11]
	v_mfma_f32_16x16x32_bf16 v[0:3], v[196:199], v[238:241], v[0:3]
	s_setprio 0
	s_barrier
	s_mov_b32 m0, s17
	s_nop 0
	global_load_lds_dwordx4 v[162:163], off
	s_mov_b32 m0, s19
	s_nop 0
	global_load_lds_dwordx4 v[200:201], off
	s_add_i32 s50, 0, 0x18000
	s_add_i32 s51, 0, 0x1c000
	v_add_u32_e32 v180, s50, v164
	v_add_u32_e32 v196, s51, v164
	ds_read_b128 v[168:171], v180
	ds_read_b128 v[172:175], v180 offset:1024
	ds_read_b128 v[176:179], v180 offset:2048
	ds_read_b128 v[180:183], v180 offset:3072
	ds_read_b128 v[184:187], v196
	ds_read_b128 v[188:191], v196 offset:1024
	ds_read_b128 v[192:195], v196 offset:2048
	ds_read_b128 v[196:199], v196 offset:3072
	s_add_u32 s24, s24, 0x40000
	s_addc_u32 s25, s25, 0
	s_mov_b32 m0, s36
	v_lshl_add_u64 v[204:205], s[24:25], 0, v[134:135]
	ds_read_b128 v[210:213], v167 offset:32768
	ds_read_b128 v[214:217], v167 offset:33792
	ds_read_b128 v[218:221], v167 offset:34816
	ds_read_b128 v[222:225], v167 offset:35840
	ds_read_b128 v[226:229], v167 offset:36864
	ds_read_b128 v[230:233], v167 offset:37888
	ds_read_b128 v[234:237], v167 offset:38912
	ds_read_b128 v[238:241], v167 offset:39936
	global_load_lds_dwordx4 v[204:205], off
	v_lshl_add_u64 v[204:205], s[24:25], 0, v[130:131]
	s_mov_b32 m0, s37
	s_nop 0
	global_load_lds_dwordx4 v[204:205], off
	s_waitcnt vmcnt(8)
	s_waitcnt lgkmcnt(0)
	s_barrier
	s_setprio 1
	s_waitcnt lgkmcnt(0)
	v_mfma_f32_16x16x32_bf16 v[124:127], v[168:171], v[210:213], v[124:127]
	v_mfma_f32_16x16x32_bf16 v[116:119], v[176:179], v[210:213], v[116:119]
	v_mfma_f32_16x16x32_bf16 v[108:111], v[168:171], v[218:221], v[108:111]
	v_mfma_f32_16x16x32_bf16 v[100:103], v[176:179], v[218:221], v[100:103]
	v_mfma_f32_16x16x32_bf16 v[92:95], v[168:171], v[226:229], v[92:95]
	v_mfma_f32_16x16x32_bf16 v[84:87], v[176:179], v[226:229], v[84:87]
	v_mfma_f32_16x16x32_bf16 v[76:79], v[168:171], v[234:237], v[76:79]
	v_mfma_f32_16x16x32_bf16 v[68:71], v[176:179], v[234:237], v[68:71]
	v_mfma_f32_16x16x32_bf16 v[124:127], v[172:175], v[214:217], v[124:127]
	v_mfma_f32_16x16x32_bf16 v[116:119], v[180:183], v[214:217], v[116:119]
	v_mfma_f32_16x16x32_bf16 v[108:111], v[172:175], v[222:225], v[108:111]
	v_mfma_f32_16x16x32_bf16 v[100:103], v[180:183], v[222:225], v[100:103]
	v_mfma_f32_16x16x32_bf16 v[92:95], v[172:175], v[230:233], v[92:95]
	v_mfma_f32_16x16x32_bf16 v[84:87], v[180:183], v[230:233], v[84:87]
	v_mfma_f32_16x16x32_bf16 v[76:79], v[172:175], v[238:241], v[76:79]
	v_mfma_f32_16x16x32_bf16 v[68:71], v[180:183], v[238:241], v[68:71]
	s_setprio 0
	s_setprio 1
	v_mfma_f32_16x16x32_bf16 v[120:123], v[184:187], v[210:213], v[120:123]
	v_mfma_f32_16x16x32_bf16 v[112:115], v[192:195], v[210:213], v[112:115]
	v_mfma_f32_16x16x32_bf16 v[104:107], v[184:187], v[218:221], v[104:107]
	v_mfma_f32_16x16x32_bf16 v[96:99], v[192:195], v[218:221], v[96:99]
	v_mfma_f32_16x16x32_bf16 v[88:91], v[184:187], v[226:229], v[88:91]
	v_mfma_f32_16x16x32_bf16 v[80:83], v[192:195], v[226:229], v[80:83]
	v_mfma_f32_16x16x32_bf16 v[72:75], v[184:187], v[234:237], v[72:75]
	v_mfma_f32_16x16x32_bf16 v[64:67], v[192:195], v[234:237], v[64:67]
	v_mfma_f32_16x16x32_bf16 v[120:123], v[188:191], v[214:217], v[120:123]
	v_mfma_f32_16x16x32_bf16 v[112:115], v[196:199], v[214:217], v[112:115]
	v_mfma_f32_16x16x32_bf16 v[104:107], v[188:191], v[222:225], v[104:107]
	v_mfma_f32_16x16x32_bf16 v[96:99], v[196:199], v[222:225], v[96:99]
	v_mfma_f32_16x16x32_bf16 v[88:91], v[188:191], v[230:233], v[88:91]
	v_mfma_f32_16x16x32_bf16 v[80:83], v[196:199], v[230:233], v[80:83]
	v_mfma_f32_16x16x32_bf16 v[72:75], v[188:191], v[238:241], v[72:75]
	v_mfma_f32_16x16x32_bf16 v[64:67], v[196:199], v[238:241], v[64:67]
	s_setprio 0
	s_barrier
	s_add_u32 s24, s22, 0x8000
	s_addc_u32 s25, s23, 0
	s_add_i32 s50, s50, s33
	v_lshl_add_u64 v[204:205], s[24:25], 0, v[132:133]
	s_mov_b32 m0, s50
	ds_read_b128 v[210:213], v167 offset:49152
	ds_read_b128 v[214:217], v167 offset:50176
	ds_read_b128 v[218:221], v167 offset:51200
	ds_read_b128 v[222:225], v167 offset:52224
	ds_read_b128 v[226:229], v167 offset:53248
	ds_read_b128 v[230:233], v167 offset:54272
	ds_read_b128 v[234:237], v167 offset:55296
	ds_read_b128 v[238:241], v167 offset:56320
	global_load_lds_dwordx4 v[204:205], off
	s_add_i32 m0, s50, 0x2000
	s_add_u32 s22, s22, 0xc000
	v_lshl_add_u64 v[204:205], s[24:25], 0, v[128:129]
	s_addc_u32 s23, s23, 0
	s_add_i32 s24, s51, s33
	global_load_lds_dwordx4 v[204:205], off
	v_lshl_add_u64 v[204:205], s[22:23], 0, v[132:133]
	s_mov_b32 m0, s24
	v_lshl_add_u64 v[162:163], v[162:163], 0, s[4:5]
	global_load_lds_dwordx4 v[204:205], off
	v_lshl_add_u64 v[204:205], s[22:23], 0, v[128:129]
	s_add_i32 m0, s24, 0x2000
	s_nop 0
	global_load_lds_dwordx4 v[204:205], off
	s_mov_b32 m0, s40
	s_nop 0
	global_load_lds_dwordx4 v[162:163], off
	v_lshl_add_u64 v[162:163], v[200:201], 0, s[4:5]
	s_mov_b32 m0, s41
	s_nop 0
	global_load_lds_dwordx4 v[162:163], off
	s_waitcnt vmcnt(8)
	s_waitcnt lgkmcnt(0)
	s_barrier
	s_setprio 1
	s_waitcnt lgkmcnt(0)
	v_mfma_f32_16x16x32_bf16 v[60:63], v[168:171], v[210:213], v[60:63]
	v_mfma_f32_16x16x32_bf16 v[52:55], v[176:179], v[210:213], v[52:55]
	v_mfma_f32_16x16x32_bf16 v[44:47], v[168:171], v[218:221], v[44:47]
	v_mfma_f32_16x16x32_bf16 v[36:39], v[176:179], v[218:221], v[36:39]
	v_mfma_f32_16x16x32_bf16 v[28:31], v[168:171], v[226:229], v[28:31]
	v_mfma_f32_16x16x32_bf16 v[20:23], v[176:179], v[226:229], v[20:23]
	v_mfma_f32_16x16x32_bf16 v[12:15], v[168:171], v[234:237], v[12:15]
	v_mfma_f32_16x16x32_bf16 v[4:7], v[176:179], v[234:237], v[4:7]
	v_mfma_f32_16x16x32_bf16 v[60:63], v[172:175], v[214:217], v[60:63]
	v_mfma_f32_16x16x32_bf16 v[52:55], v[180:183], v[214:217], v[52:55]
	v_mfma_f32_16x16x32_bf16 v[44:47], v[172:175], v[222:225], v[44:47]
	v_mfma_f32_16x16x32_bf16 v[36:39], v[180:183], v[222:225], v[36:39]
	v_mfma_f32_16x16x32_bf16 v[28:31], v[172:175], v[230:233], v[28:31]
	v_mfma_f32_16x16x32_bf16 v[20:23], v[180:183], v[230:233], v[20:23]
	v_mfma_f32_16x16x32_bf16 v[12:15], v[172:175], v[238:241], v[12:15]
	v_mfma_f32_16x16x32_bf16 v[4:7], v[180:183], v[238:241], v[4:7]
	s_setprio 0
	s_setprio 1
	v_mfma_f32_16x16x32_bf16 v[56:59], v[184:187], v[210:213], v[56:59]
	v_mfma_f32_16x16x32_bf16 v[48:51], v[192:195], v[210:213], v[48:51]
	v_mfma_f32_16x16x32_bf16 v[40:43], v[184:187], v[218:221], v[40:43]
	v_mfma_f32_16x16x32_bf16 v[32:35], v[192:195], v[218:221], v[32:35]
	v_mfma_f32_16x16x32_bf16 v[24:27], v[184:187], v[226:229], v[24:27]
	v_mfma_f32_16x16x32_bf16 v[16:19], v[192:195], v[226:229], v[16:19]
	v_mfma_f32_16x16x32_bf16 v[8:11], v[184:187], v[234:237], v[8:11]
	v_mfma_f32_16x16x32_bf16 v[0:3], v[192:195], v[234:237], v[0:3]
	v_mfma_f32_16x16x32_bf16 v[56:59], v[188:191], v[214:217], v[56:59]
	v_mfma_f32_16x16x32_bf16 v[48:51], v[196:199], v[214:217], v[48:51]
	v_mfma_f32_16x16x32_bf16 v[40:43], v[188:191], v[222:225], v[40:43]
	v_mfma_f32_16x16x32_bf16 v[32:35], v[196:199], v[222:225], v[32:35]
	v_mfma_f32_16x16x32_bf16 v[24:27], v[188:191], v[230:233], v[24:27]
	v_mfma_f32_16x16x32_bf16 v[16:19], v[196:199], v[230:233], v[16:19]
	v_mfma_f32_16x16x32_bf16 v[8:11], v[188:191], v[238:241], v[8:11]
	v_mfma_f32_16x16x32_bf16 v[0:3], v[196:199], v[238:241], v[0:3]
	s_setprio 0
	s_barrier
	s_add_i32 s49, s49, 2
	s_add_u32 s47, s47, 0x10000
	s_addc_u32 s48, s48, 0
	s_add_u32 s20, s20, 0x100
	s_addc_u32 s21, s21, 0
	s_cmp_gt_u32 s49, 13
	s_cbranch_scc0 .LBB0_1563
	s_and_b64 vcc, exec, s[6:7]
	s_cbranch_vccz .LBB0_1566
	s_barrier
